# top-k cross-lane argmax combine: the three tie-break steps (row_ror 8, permlane16/32 swap) use plain compares + SALU and/or instead of exec-masked blocks; on top of version 47
# speedup vs baseline: 1.0304x; 1.0023x over previous
.LBB0_1403:
	v_max_f32_e32 v36, v93, v93
	v_cmp_lt_f32_e32 vcc, -2.0, v93
	v_max_f32_e32 v36, -2.0, v36
	v_mov_b32_e32 v42, 0
	v_max_f32_e32 v37, v56, v56
	v_cndmask_b32_e32 v35, v174, v92, vcc
	v_mov_b32_e32 v252, v54
	v_cmp_gt_f32_e32 vcc, v95, v36
	v_cmp_gt_f32_e64 s[8:9], v57, v37
	v_max_f32_e32 v36, v36, v95
	v_max_f32_e32 v37, v37, v57
	v_cndmask_b32_e32 v35, v35, v94, vcc
	v_cndmask_b32_e64 v252, v252, v55, s[8:9]
	v_cmp_gt_f32_e32 vcc, v64, v36
	v_cmp_gt_f32_e64 s[8:9], v48, v37
	v_max_f32_e32 v36, v36, v64
	v_max_f32_e32 v37, v37, v48
	v_cndmask_b32_e32 v35, v35, v62, vcc
	v_cndmask_b32_e64 v252, v252, v46, s[8:9]
	v_cmp_gt_f32_e32 vcc, v63, v36
	v_cmp_gt_f32_e64 s[8:9], v49, v37
	v_max_f32_e32 v36, v36, v63
	v_max_f32_e32 v37, v37, v49
	v_cndmask_b32_e32 v35, v35, v1, vcc
	v_cndmask_b32_e64 v252, v252, v47, s[8:9]
	v_cmp_gt_f32_e32 vcc, v76, v36
	v_cmp_gt_f32_e64 s[8:9], v40, v37
	v_max_f32_e32 v36, v36, v76
	v_max_f32_e32 v37, v37, v40
	v_cndmask_b32_e32 v35, v35, v66, vcc
	v_cndmask_b32_e64 v252, v252, v38, s[8:9]
	v_cmp_gt_f32_e32 vcc, v67, v36
	v_cmp_gt_f32_e64 s[8:9], v41, v37
	v_max_f32_e32 v36, v36, v67
	v_max_f32_e32 v37, v37, v41
	v_cndmask_b32_e32 v35, v35, v65, vcc
	v_cndmask_b32_e64 v252, v252, v39, s[8:9]
	v_cmp_gt_f32_e32 vcc, v70, v36
	v_cmp_gt_f32_e64 s[8:9], v32, v37
	v_max_f32_e32 v36, v36, v70
	v_max_f32_e32 v37, v37, v32
	v_cndmask_b32_e32 v35, v35, v68, vcc
	v_cndmask_b32_e64 v252, v252, v30, s[8:9]
	v_cmp_gt_f32_e32 vcc, v71, v36
	v_cmp_gt_f32_e64 s[8:9], v33, v37
	v_max_f32_e32 v36, v36, v71
	v_max_f32_e32 v37, v37, v33
	v_cndmask_b32_e32 v35, v35, v69, vcc
	v_cndmask_b32_e64 v252, v252, v31, s[8:9]
	v_cmp_gt_f32_e32 vcc, v37, v36
	v_max_f32_e32 v253, v36, v37
	s_nop 0
	v_cndmask_b32_e32 v36, v35, v252, vcc
	v_mov_b32_e32 v35, v253
	v_mov_b32_e32 v37, 0
	v_mov_b32_dpp v42, v36 row_ror:8 row_mask:0xf bank_mask:0xf
	s_nop 0
	v_mov_b32_dpp v37, v35 row_ror:8 row_mask:0xf bank_mask:0xf
	v_cmp_lt_f32_e64 s[12:13], v35, v37
	v_cmp_eq_f32_e32 vcc, v35, v37
	v_cmp_lt_i32_e64 s[8:9], v42, v36
	s_and_b64 s[8:9], vcc, s[8:9]
	s_or_b64 s[12:13], s[12:13], s[8:9]
	v_cndmask_b32_e64 v35, v35, v37, s[12:13]
	v_cndmask_b32_e64 v36, v36, v42, s[12:13]
	v_mov_b32_e32 v37, v35
	s_nop 1
	v_permlane16_swap_b32_e32 v35, v37
	v_mov_b32_e32 v42, v36
	s_nop 1
	v_permlane16_swap_b32_e32 v36, v42
	v_cmp_gt_f32_e64 s[8:9], v37, v35
	v_cmp_eq_f32_e32 vcc, v37, v35
	v_cmp_lt_i32_e64 s[12:13], v42, v36
	s_and_b64 s[12:13], vcc, s[12:13]
	s_or_b64 s[8:9], s[8:9], s[12:13]
	v_cndmask_b32_e64 v37, v35, v37, s[8:9]
	v_cndmask_b32_e64 v36, v36, v42, s[8:9]
	v_mov_b32_e32 v42, v37
	s_nop 1
	v_permlane32_swap_b32_e32 v37, v42
	v_mov_b32_e32 v35, v36
	s_nop 1
	v_permlane32_swap_b32_e32 v36, v35
	v_cmp_gt_f32_e64 s[14:15], v42, v37
	v_cmp_eq_f32_e32 vcc, v42, v37
	v_cmp_lt_i32_e64 s[8:9], v35, v36
	s_and_b64 s[8:9], vcc, s[8:9]
	s_or_b64 s[14:15], s[14:15], s[8:9]
	v_cndmask_b32_e64 v37, v37, v42, s[14:15]
	v_cmp_le_f32_e32 vcc, 0, v37
	s_cmp_eq_u64 vcc, 0
	s_cselect_b64 s[12:13], -1, 0
	s_cbranch_vccz .LBB0_1415
	v_cmp_lt_u32_e64 s[8:9], s7, v34
	v_cndmask_b32_e64 v35, v36, v35, s[14:15]
	s_and_b64 s[14:15], s[8:9], vcc
	s_and_saveexec_b64 s[8:9], s[14:15]
	s_cbranch_execz .LBB0_1414
	v_bfe_u32 v37, v35, 5, 2
	v_lshlrev_b32_e64 v36, v35, 1
	v_cmp_eq_u32_e32 vcc, 0, v37
	s_nop 1
	v_cndmask_b32_e32 v42, 0, v36, vcc
	v_cmp_eq_u32_e32 vcc, 1, v37
	v_or_b32_e32 v26, v42, v26
	s_nop 0
	v_cndmask_b32_e32 v42, 0, v36, vcc
	v_cmp_eq_u32_e32 vcc, 2, v37
	v_or_b32_e32 v27, v42, v27
	s_nop 0
	v_cndmask_b32_e32 v42, 0, v36, vcc
	v_cmp_eq_u32_e32 vcc, 3, v37
	v_or_b32_e32 v28, v42, v28
	s_nop 0
	v_cndmask_b32_e32 v36, 0, v36, vcc
	v_or_b32_e32 v29, v36, v29
